# GEMM loops 2-6: redundant s_waitcnt lgkmcnt(0) after the phase barrier removed (on v063)
# baseline (speedup 1.0000x reference)
.LBB0_728:
	s_add_u32 s86, s38, s8
	s_addc_u32 s87, s39, s9
	s_add_u32 s86, s86, 0x158080
	s_addc_u32 s87, s87, 0
	s_add_u32 s16, s38, s8
	s_addc_u32 s17, s39, s9
	s_add_u32 s16, s16, 0x100
	s_addc_u32 s17, s17, 0
	s_add_u32 s34, s41, s8
	s_addc_u32 s64, s10, s9
	s_add_i32 s65, 0, 0x10000
	s_cmpk_eq_i32 s8, 0x2a00
	s_cselect_b32 s49, s53, s17
	s_cselect_b32 s48, s52, s16
	s_cselect_b32 s17, s61, s64
	s_cselect_b32 s16, s60, s34
	s_add_i32 s34, 0, 0x14000
	v_add_u32_e32 v150, s65, v234
	v_add_u32_e32 v166, s34, v234
	ds_read_b128 v[138:141], v150
	ds_read_b128 v[142:145], v150 offset:1024
	ds_read_b128 v[146:149], v150 offset:2048
	ds_read_b128 v[150:153], v150 offset:3072
	ds_read_b128 v[154:157], v166
	ds_read_b128 v[158:161], v166 offset:1024
	ds_read_b128 v[162:165], v166 offset:2048
	ds_read_b128 v[166:169], v166 offset:3072
	s_add_i32 m0, s67, 0xc000
	ds_read_b128 v[170:173], v238
	ds_read_b128 v[174:177], v238 offset:1024
	ds_read_b128 v[178:181], v238 offset:2048
	ds_read_b128 v[182:185], v238 offset:3072
	ds_read_b128 v[186:189], v238 offset:4096
	ds_read_b128 v[190:193], v238 offset:5120
	ds_read_b128 v[194:197], v238 offset:6144
	ds_read_b128 v[208:211], v238 offset:7168
	global_load_lds_dwordx4 v206, s[86:87]
	s_add_i32 m0, s67, 0xe000
	s_nop 0
	global_load_lds_dwordx4 v204, s[86:87]
	s_waitcnt vmcnt(8)
	s_waitcnt lgkmcnt(0)
	s_barrier
	v_mfma_f32_16x16x32_bf16 v[6:9], v[138:141], v[170:173], v[6:9]
	v_mfma_f32_16x16x32_bf16 v[130:133], v[146:149], v[170:173], v[130:133]
	v_mfma_f32_16x16x32_bf16 v[126:129], v[138:141], v[178:181], v[126:129]
	v_mfma_f32_16x16x32_bf16 v[122:125], v[146:149], v[178:181], v[122:125]
	v_mfma_f32_16x16x32_bf16 v[118:121], v[138:141], v[186:189], v[118:121]
	v_mfma_f32_16x16x32_bf16 v[114:117], v[146:149], v[186:189], v[114:117]
	v_mfma_f32_16x16x32_bf16 v[110:113], v[138:141], v[194:197], v[110:113]
	v_mfma_f32_16x16x32_bf16 v[106:109], v[146:149], v[194:197], v[106:109]
	v_mfma_f32_16x16x32_bf16 v[6:9], v[142:145], v[174:177], v[6:9]
	v_mfma_f32_16x16x32_bf16 v[130:133], v[150:153], v[174:177], v[130:133]
	v_mfma_f32_16x16x32_bf16 v[126:129], v[142:145], v[182:185], v[126:129]
	v_mfma_f32_16x16x32_bf16 v[122:125], v[150:153], v[182:185], v[122:125]
	v_mfma_f32_16x16x32_bf16 v[118:121], v[142:145], v[190:193], v[118:121]
	v_mfma_f32_16x16x32_bf16 v[114:117], v[150:153], v[190:193], v[114:117]
	v_mfma_f32_16x16x32_bf16 v[110:113], v[142:145], v[208:211], v[110:113]
	v_mfma_f32_16x16x32_bf16 v[106:109], v[150:153], v[208:211], v[106:109]
	v_mfma_f32_16x16x32_bf16 v[102:105], v[154:157], v[170:173], v[102:105]
	v_mfma_f32_16x16x32_bf16 v[98:101], v[162:165], v[170:173], v[98:101]
	v_mfma_f32_16x16x32_bf16 v[94:97], v[154:157], v[178:181], v[94:97]
	v_mfma_f32_16x16x32_bf16 v[90:93], v[162:165], v[178:181], v[90:93]
	v_mfma_f32_16x16x32_bf16 v[86:89], v[154:157], v[186:189], v[86:89]
	v_mfma_f32_16x16x32_bf16 v[82:85], v[162:165], v[186:189], v[82:85]
	v_mfma_f32_16x16x32_bf16 v[78:81], v[154:157], v[194:197], v[78:81]
	v_mfma_f32_16x16x32_bf16 v[74:77], v[162:165], v[194:197], v[74:77]
	v_mfma_f32_16x16x32_bf16 v[102:105], v[158:161], v[174:177], v[102:105]
	v_mfma_f32_16x16x32_bf16 v[98:101], v[166:169], v[174:177], v[98:101]
	v_mfma_f32_16x16x32_bf16 v[94:97], v[158:161], v[182:185], v[94:97]
	v_mfma_f32_16x16x32_bf16 v[90:93], v[166:169], v[182:185], v[90:93]
	v_mfma_f32_16x16x32_bf16 v[86:89], v[158:161], v[190:193], v[86:89]
	v_mfma_f32_16x16x32_bf16 v[82:85], v[166:169], v[190:193], v[82:85]
	v_mfma_f32_16x16x32_bf16 v[78:81], v[158:161], v[208:211], v[78:81]
	v_mfma_f32_16x16x32_bf16 v[74:77], v[166:169], v[208:211], v[74:77]
	s_barrier
	s_add_i32 s64, s65, s66
	s_mov_b32 m0, s64
	ds_read_b128 v[170:173], v238 offset:16384
	ds_read_b128 v[174:177], v238 offset:17408
	ds_read_b128 v[178:181], v238 offset:18432
	ds_read_b128 v[182:185], v238 offset:19456
	ds_read_b128 v[186:189], v238 offset:20480
	ds_read_b128 v[190:193], v238 offset:21504
	ds_read_b128 v[194:197], v238 offset:22528
	ds_read_b128 v[208:211], v238 offset:23552
	global_load_lds_dwordx4 v0, s[16:17]
	s_add_i32 m0, s64, 0x2000
	s_add_u32 s64, s16, 0x158000
	s_addc_u32 s65, s17, 0
	s_add_i32 s34, s34, s66
	global_load_lds_dwordx4 v14, s[16:17]
	s_mov_b32 m0, s34
	s_add_u32 s98, s48, s96
	s_addc_u32 s99, s49, s97
	global_load_lds_dwordx4 v0, s[64:65]
	s_add_i32 m0, s34, 0x2000
	s_nop 0
	global_load_lds_dwordx4 v14, s[64:65]
	s_mov_b32 m0, s67
	s_nop 0
	global_load_lds_dwordx4 v0, s[48:49]
	s_mov_b32 m0, s68
	s_nop 0
	global_load_lds_dwordx4 v14, s[48:49]
	s_waitcnt vmcnt(8)
	s_waitcnt lgkmcnt(0)
	s_barrier
	v_mfma_f32_16x16x32_bf16 v[70:73], v[138:141], v[170:173], v[70:73]
	v_mfma_f32_16x16x32_bf16 v[66:69], v[146:149], v[170:173], v[66:69]
	v_mfma_f32_16x16x32_bf16 v[62:65], v[138:141], v[178:181], v[62:65]
	v_mfma_f32_16x16x32_bf16 v[58:61], v[146:149], v[178:181], v[58:61]
	v_mfma_f32_16x16x32_bf16 v[54:57], v[138:141], v[186:189], v[54:57]
	v_mfma_f32_16x16x32_bf16 v[50:53], v[146:149], v[186:189], v[50:53]
	v_mfma_f32_16x16x32_bf16 v[46:49], v[138:141], v[194:197], v[46:49]
	v_mfma_f32_16x16x32_bf16 v[42:45], v[146:149], v[194:197], v[42:45]
	v_mfma_f32_16x16x32_bf16 v[70:73], v[142:145], v[174:177], v[70:73]
	v_mfma_f32_16x16x32_bf16 v[66:69], v[150:153], v[174:177], v[66:69]
	v_mfma_f32_16x16x32_bf16 v[62:65], v[142:145], v[182:185], v[62:65]
	v_mfma_f32_16x16x32_bf16 v[58:61], v[150:153], v[182:185], v[58:61]
	v_mfma_f32_16x16x32_bf16 v[54:57], v[142:145], v[190:193], v[54:57]
	v_mfma_f32_16x16x32_bf16 v[50:53], v[150:153], v[190:193], v[50:53]
	v_mfma_f32_16x16x32_bf16 v[46:49], v[142:145], v[208:211], v[46:49]
	v_mfma_f32_16x16x32_bf16 v[42:45], v[150:153], v[208:211], v[42:45]
	v_mfma_f32_16x16x32_bf16 v[38:41], v[154:157], v[170:173], v[38:41]
	v_mfma_f32_16x16x32_bf16 v[34:37], v[162:165], v[170:173], v[34:37]
	v_mfma_f32_16x16x32_bf16 v[30:33], v[154:157], v[178:181], v[30:33]
	v_mfma_f32_16x16x32_bf16 v[26:29], v[162:165], v[178:181], v[26:29]
	v_mfma_f32_16x16x32_bf16 v[22:25], v[154:157], v[186:189], v[22:25]
	v_mfma_f32_16x16x32_bf16 v[18:21], v[162:165], v[186:189], v[18:21]
	v_mfma_f32_16x16x32_bf16 v[10:13], v[154:157], v[194:197], v[10:13]
	v_mfma_f32_16x16x32_bf16 v[2:5], v[162:165], v[194:197], v[2:5]
	v_mfma_f32_16x16x32_bf16 v[38:41], v[158:161], v[174:177], v[38:41]
	v_mfma_f32_16x16x32_bf16 v[34:37], v[166:169], v[174:177], v[34:37]
	v_mfma_f32_16x16x32_bf16 v[30:33], v[158:161], v[182:185], v[30:33]
	v_mfma_f32_16x16x32_bf16 v[26:29], v[166:169], v[182:185], v[26:29]
	v_mfma_f32_16x16x32_bf16 v[22:25], v[158:161], v[190:193], v[22:25]
	v_mfma_f32_16x16x32_bf16 v[18:21], v[166:169], v[190:193], v[18:21]
	v_mfma_f32_16x16x32_bf16 v[10:13], v[158:161], v[208:211], v[10:13]
	v_mfma_f32_16x16x32_bf16 v[2:5], v[166:169], v[208:211], v[2:5]
	s_barrier
	s_add_i32 s34, 0, 0x18000
	s_add_i32 s64, 0, 0x1c000
	v_add_u32_e32 v150, s34, v234
	v_add_u32_e32 v166, s64, v234
	ds_read_b128 v[138:141], v150
	ds_read_b128 v[142:145], v150 offset:1024
	ds_read_b128 v[146:149], v150 offset:2048
	ds_read_b128 v[150:153], v150 offset:3072
	ds_read_b128 v[154:157], v166
	ds_read_b128 v[158:161], v166 offset:1024
	ds_read_b128 v[162:165], v166 offset:2048
	ds_read_b128 v[166:169], v166 offset:3072
	s_add_u32 s48, s48, 0x158000
	s_addc_u32 s49, s49, 0
	s_mov_b32 m0, s69
	ds_read_b128 v[170:173], v238 offset:32768
	ds_read_b128 v[174:177], v238 offset:33792
	ds_read_b128 v[178:181], v238 offset:34816
	ds_read_b128 v[182:185], v238 offset:35840
	ds_read_b128 v[186:189], v238 offset:36864
	ds_read_b128 v[190:193], v238 offset:37888
	ds_read_b128 v[194:197], v238 offset:38912
	ds_read_b128 v[208:211], v238 offset:39936
	global_load_lds_dwordx4 v0, s[48:49]
	s_mov_b32 m0, s70
	s_nop 0
	global_load_lds_dwordx4 v14, s[48:49]
	s_waitcnt vmcnt(8)
	s_waitcnt lgkmcnt(0)
	s_barrier
	v_mfma_f32_16x16x32_bf16 v[6:9], v[138:141], v[170:173], v[6:9]
	v_mfma_f32_16x16x32_bf16 v[130:133], v[146:149], v[170:173], v[130:133]
	v_mfma_f32_16x16x32_bf16 v[126:129], v[138:141], v[178:181], v[126:129]
	v_mfma_f32_16x16x32_bf16 v[122:125], v[146:149], v[178:181], v[122:125]
	v_mfma_f32_16x16x32_bf16 v[118:121], v[138:141], v[186:189], v[118:121]
	v_mfma_f32_16x16x32_bf16 v[114:117], v[146:149], v[186:189], v[114:117]
	v_mfma_f32_16x16x32_bf16 v[110:113], v[138:141], v[194:197], v[110:113]
	v_mfma_f32_16x16x32_bf16 v[106:109], v[146:149], v[194:197], v[106:109]
	v_mfma_f32_16x16x32_bf16 v[6:9], v[142:145], v[174:177], v[6:9]
	v_mfma_f32_16x16x32_bf16 v[130:133], v[150:153], v[174:177], v[130:133]
	v_mfma_f32_16x16x32_bf16 v[126:129], v[142:145], v[182:185], v[126:129]
	v_mfma_f32_16x16x32_bf16 v[122:125], v[150:153], v[182:185], v[122:125]
	v_mfma_f32_16x16x32_bf16 v[118:121], v[142:145], v[190:193], v[118:121]
	v_mfma_f32_16x16x32_bf16 v[114:117], v[150:153], v[190:193], v[114:117]
	v_mfma_f32_16x16x32_bf16 v[110:113], v[142:145], v[208:211], v[110:113]
	v_mfma_f32_16x16x32_bf16 v[106:109], v[150:153], v[208:211], v[106:109]
	v_mfma_f32_16x16x32_bf16 v[102:105], v[154:157], v[170:173], v[102:105]
	v_mfma_f32_16x16x32_bf16 v[98:101], v[162:165], v[170:173], v[98:101]
	v_mfma_f32_16x16x32_bf16 v[94:97], v[154:157], v[178:181], v[94:97]
	v_mfma_f32_16x16x32_bf16 v[90:93], v[162:165], v[178:181], v[90:93]
	v_mfma_f32_16x16x32_bf16 v[86:89], v[154:157], v[186:189], v[86:89]
	v_mfma_f32_16x16x32_bf16 v[82:85], v[162:165], v[186:189], v[82:85]
	v_mfma_f32_16x16x32_bf16 v[78:81], v[154:157], v[194:197], v[78:81]
	v_mfma_f32_16x16x32_bf16 v[74:77], v[162:165], v[194:197], v[74:77]
	v_mfma_f32_16x16x32_bf16 v[102:105], v[158:161], v[174:177], v[102:105]
	v_mfma_f32_16x16x32_bf16 v[98:101], v[166:169], v[174:177], v[98:101]
	v_mfma_f32_16x16x32_bf16 v[94:97], v[158:161], v[182:185], v[94:97]
	v_mfma_f32_16x16x32_bf16 v[90:93], v[166:169], v[182:185], v[90:93]
	v_mfma_f32_16x16x32_bf16 v[86:89], v[158:161], v[190:193], v[86:89]
	v_mfma_f32_16x16x32_bf16 v[82:85], v[166:169], v[190:193], v[82:85]
	v_mfma_f32_16x16x32_bf16 v[78:81], v[158:161], v[208:211], v[78:81]
	v_mfma_f32_16x16x32_bf16 v[74:77], v[166:169], v[208:211], v[74:77]
	s_barrier
	s_add_i32 s34, s34, s66
	s_add_u32 s86, s16, s96
	s_addc_u32 s87, s17, s97
	s_mov_b32 m0, s34
	ds_read_b128 v[170:173], v238 offset:49152
	ds_read_b128 v[174:177], v238 offset:50176
	ds_read_b128 v[178:181], v238 offset:51200
	ds_read_b128 v[182:185], v238 offset:52224
	ds_read_b128 v[186:189], v238 offset:53248
	ds_read_b128 v[190:193], v238 offset:54272
	ds_read_b128 v[194:197], v238 offset:55296
	ds_read_b128 v[208:211], v238 offset:56320
	global_load_lds_dwordx4 v0, s[86:87]
	s_add_i32 m0, s34, 0x2000
	s_add_u32 s16, s16, 0x158080
	s_addc_u32 s17, s17, 0
	s_add_i32 s34, s64, s66
	global_load_lds_dwordx4 v14, s[86:87]
	s_mov_b32 m0, s34
	s_nop 0
	global_load_lds_dwordx4 v0, s[16:17]
	s_add_i32 m0, s34, 0x2000
	s_nop 0
	global_load_lds_dwordx4 v14, s[16:17]
	s_mov_b32 m0, s76
	s_nop 0
	global_load_lds_dwordx4 v0, s[98:99]
	s_mov_b32 m0, s77
	s_nop 0
	global_load_lds_dwordx4 v14, s[98:99]
	s_waitcnt vmcnt(8)
	s_waitcnt lgkmcnt(0)
	s_barrier
	v_mfma_f32_16x16x32_bf16 v[70:73], v[138:141], v[170:173], v[70:73]
	v_mfma_f32_16x16x32_bf16 v[66:69], v[146:149], v[170:173], v[66:69]
	v_mfma_f32_16x16x32_bf16 v[62:65], v[138:141], v[178:181], v[62:65]
	v_mfma_f32_16x16x32_bf16 v[58:61], v[146:149], v[178:181], v[58:61]
	v_mfma_f32_16x16x32_bf16 v[54:57], v[138:141], v[186:189], v[54:57]
	v_mfma_f32_16x16x32_bf16 v[50:53], v[146:149], v[186:189], v[50:53]
	v_mfma_f32_16x16x32_bf16 v[46:49], v[138:141], v[194:197], v[46:49]
	v_mfma_f32_16x16x32_bf16 v[42:45], v[146:149], v[194:197], v[42:45]
	v_mfma_f32_16x16x32_bf16 v[70:73], v[142:145], v[174:177], v[70:73]
	v_mfma_f32_16x16x32_bf16 v[66:69], v[150:153], v[174:177], v[66:69]
	v_mfma_f32_16x16x32_bf16 v[62:65], v[142:145], v[182:185], v[62:65]
	v_mfma_f32_16x16x32_bf16 v[58:61], v[150:153], v[182:185], v[58:61]
	v_mfma_f32_16x16x32_bf16 v[54:57], v[142:145], v[190:193], v[54:57]
	v_mfma_f32_16x16x32_bf16 v[50:53], v[150:153], v[190:193], v[50:53]
	v_mfma_f32_16x16x32_bf16 v[46:49], v[142:145], v[208:211], v[46:49]
	v_mfma_f32_16x16x32_bf16 v[42:45], v[150:153], v[208:211], v[42:45]
	v_mfma_f32_16x16x32_bf16 v[38:41], v[154:157], v[170:173], v[38:41]
	v_mfma_f32_16x16x32_bf16 v[34:37], v[162:165], v[170:173], v[34:37]
	v_mfma_f32_16x16x32_bf16 v[30:33], v[154:157], v[178:181], v[30:33]
	v_mfma_f32_16x16x32_bf16 v[26:29], v[162:165], v[178:181], v[26:29]
	v_mfma_f32_16x16x32_bf16 v[22:25], v[154:157], v[186:189], v[22:25]
	v_mfma_f32_16x16x32_bf16 v[18:21], v[162:165], v[186:189], v[18:21]
	v_mfma_f32_16x16x32_bf16 v[10:13], v[154:157], v[194:197], v[10:13]
	v_mfma_f32_16x16x32_bf16 v[2:5], v[162:165], v[194:197], v[2:5]
	v_mfma_f32_16x16x32_bf16 v[38:41], v[158:161], v[174:177], v[38:41]
	v_mfma_f32_16x16x32_bf16 v[34:37], v[166:169], v[174:177], v[34:37]
	v_mfma_f32_16x16x32_bf16 v[30:33], v[158:161], v[182:185], v[30:33]
	v_mfma_f32_16x16x32_bf16 v[26:29], v[166:169], v[182:185], v[26:29]
	v_mfma_f32_16x16x32_bf16 v[22:25], v[158:161], v[190:193], v[22:25]
	v_mfma_f32_16x16x32_bf16 v[18:21], v[166:169], v[190:193], v[18:21]
	v_mfma_f32_16x16x32_bf16 v[10:13], v[158:161], v[208:211], v[10:13]
	v_mfma_f32_16x16x32_bf16 v[2:5], v[166:169], v[208:211], v[2:5]
	s_barrier
	s_add_i32 s11, s11, 2
	s_add_u32 s8, s8, 0x100
	s_addc_u32 s9, s9, 0
	s_cmpk_gt_u32 s11, 0x53
	s_cbranch_scc0 .LBB0_728
	s_and_b64 vcc, exec, s[28:29]
	s_cbranch_vccz .LBB0_731
	s_barrier

.LBB0_1045:
	s_add_u32 s46, s6, 0xfff80080
	s_addc_u32 s47, s7, -1
	s_add_i32 s52, 0, 0x10000
	s_cmp_eq_u32 s41, 28
	s_cselect_b32 s49, s9, s47
	s_cselect_b32 s48, s29, s46
	v_add_u32_e32 v0, s52, v149
	s_cselect_b32 s47, s31, s40
	s_cselect_b32 s46, s34, s39
	s_add_i32 s60, 0, 0x14000
	ds_read_b128 v[134:137], v0
	ds_read_b128 v[138:141], v0 offset:1024
	ds_read_b128 v[160:163], v0 offset:2048
	ds_read_b128 v[164:167], v0 offset:3072
	v_add_u32_e32 v0, s60, v149
	ds_read_b128 v[168:171], v0
	ds_read_b128 v[172:175], v0 offset:1024
	ds_read_b128 v[176:179], v0 offset:2048
	ds_read_b128 v[188:191], v0 offset:3072
	s_add_i32 m0, s63, 0xc000
	ds_read_b128 v[192:195], v186
	ds_read_b128 v[204:207], v186 offset:1024
	ds_read_b128 v[208:211], v186 offset:2048
	ds_read_b128 v[212:215], v186 offset:3072
	ds_read_b128 v[216:219], v186 offset:4096
	ds_read_b128 v[220:223], v186 offset:5120
	ds_read_b128 v[224:227], v186 offset:6144
	ds_read_b128 v[234:237], v186 offset:7168
	global_load_lds_dwordx4 v158, s[6:7]
	s_add_i32 m0, s63, 0xe000
	s_nop 0
	global_load_lds_dwordx4 v156, s[6:7]
	s_waitcnt vmcnt(8)
	s_waitcnt lgkmcnt(0)
	s_barrier
	v_mfma_f32_16x16x32_bf16 v[130:133], v[134:137], v[192:195], v[130:133]
	v_mfma_f32_16x16x32_bf16 v[126:129], v[160:163], v[192:195], v[126:129]
	v_mfma_f32_16x16x32_bf16 v[114:117], v[134:137], v[208:211], v[114:117]
	v_mfma_f32_16x16x32_bf16 v[110:113], v[160:163], v[208:211], v[110:113]
	v_mfma_f32_16x16x32_bf16 v[98:101], v[134:137], v[216:219], v[98:101]
	v_mfma_f32_16x16x32_bf16 v[94:97], v[160:163], v[216:219], v[94:97]
	v_mfma_f32_16x16x32_bf16 v[82:85], v[134:137], v[224:227], v[82:85]
	v_mfma_f32_16x16x32_bf16 v[78:81], v[160:163], v[224:227], v[78:81]
	v_mfma_f32_16x16x32_bf16 v[130:133], v[138:141], v[204:207], v[130:133]
	v_mfma_f32_16x16x32_bf16 v[126:129], v[164:167], v[204:207], v[126:129]
	v_mfma_f32_16x16x32_bf16 v[114:117], v[138:141], v[212:215], v[114:117]
	v_mfma_f32_16x16x32_bf16 v[110:113], v[164:167], v[212:215], v[110:113]
	v_mfma_f32_16x16x32_bf16 v[98:101], v[138:141], v[220:223], v[98:101]
	v_mfma_f32_16x16x32_bf16 v[94:97], v[164:167], v[220:223], v[94:97]
	v_mfma_f32_16x16x32_bf16 v[82:85], v[138:141], v[234:237], v[82:85]
	v_mfma_f32_16x16x32_bf16 v[78:81], v[164:167], v[234:237], v[78:81]
	v_mfma_f32_16x16x32_bf16 v[122:125], v[168:171], v[192:195], v[122:125]
	v_mfma_f32_16x16x32_bf16 v[118:121], v[176:179], v[192:195], v[118:121]
	v_mfma_f32_16x16x32_bf16 v[106:109], v[168:171], v[208:211], v[106:109]
	v_mfma_f32_16x16x32_bf16 v[102:105], v[176:179], v[208:211], v[102:105]
	v_mfma_f32_16x16x32_bf16 v[90:93], v[168:171], v[216:219], v[90:93]
	v_mfma_f32_16x16x32_bf16 v[86:89], v[176:179], v[216:219], v[86:89]
	v_mfma_f32_16x16x32_bf16 v[74:77], v[168:171], v[224:227], v[74:77]
	v_mfma_f32_16x16x32_bf16 v[70:73], v[176:179], v[224:227], v[70:73]
	v_mfma_f32_16x16x32_bf16 v[122:125], v[172:175], v[204:207], v[122:125]
	v_mfma_f32_16x16x32_bf16 v[118:121], v[188:191], v[204:207], v[118:121]
	v_mfma_f32_16x16x32_bf16 v[106:109], v[172:175], v[212:215], v[106:109]
	v_mfma_f32_16x16x32_bf16 v[102:105], v[188:191], v[212:215], v[102:105]
	v_mfma_f32_16x16x32_bf16 v[90:93], v[172:175], v[220:223], v[90:93]
	v_mfma_f32_16x16x32_bf16 v[86:89], v[188:191], v[220:223], v[86:89]
	v_mfma_f32_16x16x32_bf16 v[74:77], v[172:175], v[234:237], v[74:77]
	v_mfma_f32_16x16x32_bf16 v[70:73], v[188:191], v[234:237], v[70:73]
	s_barrier
	s_add_i32 s52, s52, s56
	s_mov_b32 m0, s52
	ds_read_b128 v[192:195], v186 offset:16384
	ds_read_b128 v[204:207], v186 offset:17408
	ds_read_b128 v[208:211], v186 offset:18432
	ds_read_b128 v[212:215], v186 offset:19456
	ds_read_b128 v[216:219], v186 offset:20480
	ds_read_b128 v[220:223], v186 offset:21504
	ds_read_b128 v[224:227], v186 offset:22528
	ds_read_b128 v[234:237], v186 offset:23552
	global_load_lds_dwordx4 v142, s[46:47]
	s_add_i32 m0, s52, 0x2000
	s_add_u32 s52, s46, 0x80000
	s_addc_u32 s53, s47, 0
	s_add_i32 s60, s60, s56
	global_load_lds_dwordx4 v146, s[46:47]
	s_mov_b32 m0, s60
	s_add_u32 s98, s48, s96
	s_addc_u32 s99, s49, s97
	global_load_lds_dwordx4 v142, s[52:53]
	s_add_i32 m0, s60, 0x2000
	s_nop 0
	global_load_lds_dwordx4 v146, s[52:53]
	s_mov_b32 m0, s63
	s_nop 0
	global_load_lds_dwordx4 v14, s[48:49]
	s_mov_b32 m0, s66
	s_nop 0
	global_load_lds_dwordx4 v144, s[48:49]
	s_waitcnt vmcnt(8)
	s_waitcnt lgkmcnt(0)
	s_barrier
	v_mfma_f32_16x16x32_bf16 v[66:69], v[134:137], v[192:195], v[66:69]
	v_mfma_f32_16x16x32_bf16 v[62:65], v[160:163], v[192:195], v[62:65]
	v_mfma_f32_16x16x32_bf16 v[50:53], v[134:137], v[208:211], v[50:53]
	v_mfma_f32_16x16x32_bf16 v[46:49], v[160:163], v[208:211], v[46:49]
	v_mfma_f32_16x16x32_bf16 v[34:37], v[134:137], v[216:219], v[34:37]
	v_mfma_f32_16x16x32_bf16 v[30:33], v[160:163], v[216:219], v[30:33]
	v_mfma_f32_16x16x32_bf16 v[18:21], v[134:137], v[224:227], v[18:21]
	v_mfma_f32_16x16x32_bf16 v[10:13], v[160:163], v[224:227], v[10:13]
	v_mfma_f32_16x16x32_bf16 v[66:69], v[138:141], v[204:207], v[66:69]
	v_mfma_f32_16x16x32_bf16 v[62:65], v[164:167], v[204:207], v[62:65]
	v_mfma_f32_16x16x32_bf16 v[50:53], v[138:141], v[212:215], v[50:53]
	v_mfma_f32_16x16x32_bf16 v[46:49], v[164:167], v[212:215], v[46:49]
	v_mfma_f32_16x16x32_bf16 v[34:37], v[138:141], v[220:223], v[34:37]
	v_mfma_f32_16x16x32_bf16 v[30:33], v[164:167], v[220:223], v[30:33]
	v_mfma_f32_16x16x32_bf16 v[18:21], v[138:141], v[234:237], v[18:21]
	v_mfma_f32_16x16x32_bf16 v[10:13], v[164:167], v[234:237], v[10:13]
	v_mfma_f32_16x16x32_bf16 v[58:61], v[168:171], v[192:195], v[58:61]
	v_mfma_f32_16x16x32_bf16 v[54:57], v[176:179], v[192:195], v[54:57]
	v_mfma_f32_16x16x32_bf16 v[42:45], v[168:171], v[208:211], v[42:45]
	v_mfma_f32_16x16x32_bf16 v[38:41], v[176:179], v[208:211], v[38:41]
	v_mfma_f32_16x16x32_bf16 v[26:29], v[168:171], v[216:219], v[26:29]
	v_mfma_f32_16x16x32_bf16 v[22:25], v[176:179], v[216:219], v[22:25]
	v_mfma_f32_16x16x32_bf16 v[6:9], v[168:171], v[224:227], v[6:9]
	v_mfma_f32_16x16x32_bf16 v[2:5], v[176:179], v[224:227], v[2:5]
	v_mfma_f32_16x16x32_bf16 v[58:61], v[172:175], v[204:207], v[58:61]
	v_mfma_f32_16x16x32_bf16 v[54:57], v[188:191], v[204:207], v[54:57]
	v_mfma_f32_16x16x32_bf16 v[42:45], v[172:175], v[212:215], v[42:45]
	v_mfma_f32_16x16x32_bf16 v[38:41], v[188:191], v[212:215], v[38:41]
	v_mfma_f32_16x16x32_bf16 v[26:29], v[172:175], v[220:223], v[26:29]
	v_mfma_f32_16x16x32_bf16 v[22:25], v[188:191], v[220:223], v[22:25]
	v_mfma_f32_16x16x32_bf16 v[6:9], v[172:175], v[234:237], v[6:9]
	v_mfma_f32_16x16x32_bf16 v[2:5], v[188:191], v[234:237], v[2:5]
	s_barrier
	s_add_i32 s52, 0, 0x18000
	v_add_u32_e32 v0, s52, v149
	s_add_i32 s53, 0, 0x1c000
	ds_read_b128 v[134:137], v0
	ds_read_b128 v[138:141], v0 offset:1024
	ds_read_b128 v[160:163], v0 offset:2048
	ds_read_b128 v[164:167], v0 offset:3072
	v_add_u32_e32 v0, s53, v149
	ds_read_b128 v[168:171], v0
	ds_read_b128 v[172:175], v0 offset:1024
	ds_read_b128 v[176:179], v0 offset:2048
	ds_read_b128 v[188:191], v0 offset:3072
	s_add_u32 s48, s48, 0x80000
	s_addc_u32 s49, s49, 0
	s_mov_b32 m0, s67
	ds_read_b128 v[192:195], v186 offset:32768
	ds_read_b128 v[204:207], v186 offset:33792
	ds_read_b128 v[208:211], v186 offset:34816
	ds_read_b128 v[212:215], v186 offset:35840
	ds_read_b128 v[216:219], v186 offset:36864
	ds_read_b128 v[220:223], v186 offset:37888
	ds_read_b128 v[224:227], v186 offset:38912
	ds_read_b128 v[234:237], v186 offset:39936
	global_load_lds_dwordx4 v14, s[48:49]
	s_mov_b32 m0, s68
	s_nop 0
	global_load_lds_dwordx4 v144, s[48:49]
	s_waitcnt vmcnt(8)
	s_waitcnt lgkmcnt(0)
	s_barrier
	v_mfma_f32_16x16x32_bf16 v[130:133], v[134:137], v[192:195], v[130:133]
	v_mfma_f32_16x16x32_bf16 v[126:129], v[160:163], v[192:195], v[126:129]
	v_mfma_f32_16x16x32_bf16 v[114:117], v[134:137], v[208:211], v[114:117]
	v_mfma_f32_16x16x32_bf16 v[110:113], v[160:163], v[208:211], v[110:113]
	v_mfma_f32_16x16x32_bf16 v[98:101], v[134:137], v[216:219], v[98:101]
	v_mfma_f32_16x16x32_bf16 v[94:97], v[160:163], v[216:219], v[94:97]
	v_mfma_f32_16x16x32_bf16 v[82:85], v[134:137], v[224:227], v[82:85]
	v_mfma_f32_16x16x32_bf16 v[78:81], v[160:163], v[224:227], v[78:81]
	v_mfma_f32_16x16x32_bf16 v[130:133], v[138:141], v[204:207], v[130:133]
	v_mfma_f32_16x16x32_bf16 v[126:129], v[164:167], v[204:207], v[126:129]
	v_mfma_f32_16x16x32_bf16 v[114:117], v[138:141], v[212:215], v[114:117]
	v_mfma_f32_16x16x32_bf16 v[110:113], v[164:167], v[212:215], v[110:113]
	v_mfma_f32_16x16x32_bf16 v[98:101], v[138:141], v[220:223], v[98:101]
	v_mfma_f32_16x16x32_bf16 v[94:97], v[164:167], v[220:223], v[94:97]
	v_mfma_f32_16x16x32_bf16 v[82:85], v[138:141], v[234:237], v[82:85]
	v_mfma_f32_16x16x32_bf16 v[78:81], v[164:167], v[234:237], v[78:81]
	v_mfma_f32_16x16x32_bf16 v[122:125], v[168:171], v[192:195], v[122:125]
	v_mfma_f32_16x16x32_bf16 v[118:121], v[176:179], v[192:195], v[118:121]
	v_mfma_f32_16x16x32_bf16 v[106:109], v[168:171], v[208:211], v[106:109]
	v_mfma_f32_16x16x32_bf16 v[102:105], v[176:179], v[208:211], v[102:105]
	v_mfma_f32_16x16x32_bf16 v[90:93], v[168:171], v[216:219], v[90:93]
	v_mfma_f32_16x16x32_bf16 v[86:89], v[176:179], v[216:219], v[86:89]
	v_mfma_f32_16x16x32_bf16 v[74:77], v[168:171], v[224:227], v[74:77]
	v_mfma_f32_16x16x32_bf16 v[70:73], v[176:179], v[224:227], v[70:73]
	v_mfma_f32_16x16x32_bf16 v[122:125], v[172:175], v[204:207], v[122:125]
	v_mfma_f32_16x16x32_bf16 v[118:121], v[188:191], v[204:207], v[118:121]
	v_mfma_f32_16x16x32_bf16 v[106:109], v[172:175], v[212:215], v[106:109]
	v_mfma_f32_16x16x32_bf16 v[102:105], v[188:191], v[212:215], v[102:105]
	v_mfma_f32_16x16x32_bf16 v[90:93], v[172:175], v[220:223], v[90:93]
	v_mfma_f32_16x16x32_bf16 v[86:89], v[188:191], v[220:223], v[86:89]
	v_mfma_f32_16x16x32_bf16 v[74:77], v[172:175], v[234:237], v[74:77]
	v_mfma_f32_16x16x32_bf16 v[70:73], v[188:191], v[234:237], v[70:73]
	s_barrier
	s_add_i32 s48, s52, s56
	s_add_u32 s88, s46, s96
	s_addc_u32 s89, s47, s97
	s_mov_b32 m0, s48
	ds_read_b128 v[192:195], v186 offset:49152
	ds_read_b128 v[204:207], v186 offset:50176
	ds_read_b128 v[208:211], v186 offset:51200
	ds_read_b128 v[212:215], v186 offset:52224
	ds_read_b128 v[216:219], v186 offset:53248
	ds_read_b128 v[220:223], v186 offset:54272
	ds_read_b128 v[224:227], v186 offset:55296
	ds_read_b128 v[234:237], v186 offset:56320
	global_load_lds_dwordx4 v142, s[88:89]
	s_add_i32 m0, s48, 0x2000
	s_add_u32 s46, s46, 0x80080
	s_addc_u32 s47, s47, 0
	s_add_i32 s48, s53, s56
	global_load_lds_dwordx4 v146, s[88:89]
	s_mov_b32 m0, s48
	s_nop 0
	global_load_lds_dwordx4 v142, s[46:47]
	s_add_i32 m0, s48, 0x2000
	s_nop 0
	global_load_lds_dwordx4 v146, s[46:47]
	s_mov_b32 m0, s78
	s_nop 0
	global_load_lds_dwordx4 v14, s[98:99]
	s_mov_b32 m0, s79
	s_nop 0
	global_load_lds_dwordx4 v144, s[98:99]
	s_waitcnt vmcnt(8)
	s_waitcnt lgkmcnt(0)
	s_barrier
	v_mfma_f32_16x16x32_bf16 v[66:69], v[134:137], v[192:195], v[66:69]
	v_mfma_f32_16x16x32_bf16 v[62:65], v[160:163], v[192:195], v[62:65]
	v_mfma_f32_16x16x32_bf16 v[50:53], v[134:137], v[208:211], v[50:53]
	v_mfma_f32_16x16x32_bf16 v[46:49], v[160:163], v[208:211], v[46:49]
	v_mfma_f32_16x16x32_bf16 v[34:37], v[134:137], v[216:219], v[34:37]
	v_mfma_f32_16x16x32_bf16 v[30:33], v[160:163], v[216:219], v[30:33]
	v_mfma_f32_16x16x32_bf16 v[18:21], v[134:137], v[224:227], v[18:21]
	v_mfma_f32_16x16x32_bf16 v[10:13], v[160:163], v[224:227], v[10:13]
	v_mfma_f32_16x16x32_bf16 v[66:69], v[138:141], v[204:207], v[66:69]
	v_mfma_f32_16x16x32_bf16 v[62:65], v[164:167], v[204:207], v[62:65]
	v_mfma_f32_16x16x32_bf16 v[50:53], v[138:141], v[212:215], v[50:53]
	v_mfma_f32_16x16x32_bf16 v[46:49], v[164:167], v[212:215], v[46:49]
	v_mfma_f32_16x16x32_bf16 v[34:37], v[138:141], v[220:223], v[34:37]
	v_mfma_f32_16x16x32_bf16 v[30:33], v[164:167], v[220:223], v[30:33]
	v_mfma_f32_16x16x32_bf16 v[18:21], v[138:141], v[234:237], v[18:21]
	v_mfma_f32_16x16x32_bf16 v[10:13], v[164:167], v[234:237], v[10:13]
	v_mfma_f32_16x16x32_bf16 v[58:61], v[168:171], v[192:195], v[58:61]
	v_mfma_f32_16x16x32_bf16 v[54:57], v[176:179], v[192:195], v[54:57]
	v_mfma_f32_16x16x32_bf16 v[42:45], v[168:171], v[208:211], v[42:45]
	v_mfma_f32_16x16x32_bf16 v[38:41], v[176:179], v[208:211], v[38:41]
	v_mfma_f32_16x16x32_bf16 v[26:29], v[168:171], v[216:219], v[26:29]
	v_mfma_f32_16x16x32_bf16 v[22:25], v[176:179], v[216:219], v[22:25]
	v_mfma_f32_16x16x32_bf16 v[6:9], v[168:171], v[224:227], v[6:9]
	v_mfma_f32_16x16x32_bf16 v[2:5], v[176:179], v[224:227], v[2:5]
	v_mfma_f32_16x16x32_bf16 v[58:61], v[172:175], v[204:207], v[58:61]
	v_mfma_f32_16x16x32_bf16 v[54:57], v[188:191], v[204:207], v[54:57]
	v_mfma_f32_16x16x32_bf16 v[42:45], v[172:175], v[212:215], v[42:45]
	v_mfma_f32_16x16x32_bf16 v[38:41], v[188:191], v[212:215], v[38:41]
	v_mfma_f32_16x16x32_bf16 v[26:29], v[172:175], v[220:223], v[26:29]
	v_mfma_f32_16x16x32_bf16 v[22:25], v[188:191], v[220:223], v[22:25]
	v_mfma_f32_16x16x32_bf16 v[6:9], v[172:175], v[234:237], v[6:9]
	v_mfma_f32_16x16x32_bf16 v[2:5], v[188:191], v[234:237], v[2:5]
	s_barrier
	s_add_i32 s41, s41, 2
	s_add_u32 s39, s39, 0x100
	s_addc_u32 s40, s40, 0
	s_add_u32 s6, s6, 0x100
	s_addc_u32 s7, s7, 0
	s_cmp_gt_u32 s41, 29
	s_cbranch_scc0 .LBB0_1045
	s_and_b64 vcc, exec, s[22:23]
	s_cbranch_vccz .LBB0_1048
	s_barrier

.LBB0_1300:
	s_add_u32 s12, s41, s10
	s_addc_u32 s13, s44, s11
	s_add_u32 s12, s12, 0x40601100
	s_addc_u32 s13, s13, 0
	s_add_u32 s46, s39, s10
	s_addc_u32 s47, s40, s11
	s_add_i32 s48, 0, 0x10000
	v_add_u32_e32 v96, s48, v82
	ds_read_b128 v[84:87], v96
	ds_read_b128 v[88:91], v96 offset:1024
	ds_read_b128 v[92:95], v96 offset:2048
	ds_read_b128 v[96:99], v96 offset:3072
	s_cmpk_eq_i32 s10, 0x1f00
	s_cselect_b32 s15, s5, s13
	s_cselect_b32 s14, s4, s12
	s_cselect_b32 s13, s3, s47
	s_cselect_b32 s12, s2, s46
	v_lshl_add_u64 v[132:133], v[78:79], 0, s[10:11]
	s_add_i32 m0, s25, 0xc000
	ds_read_b128 v[100:103], v83
	ds_read_b128 v[104:107], v83 offset:1024
	ds_read_b128 v[108:111], v83 offset:2048
	ds_read_b128 v[112:115], v83 offset:3072
	ds_read_b128 v[116:119], v83 offset:4096
	ds_read_b128 v[120:123], v83 offset:5120
	ds_read_b128 v[124:127], v83 offset:6144
	ds_read_b128 v[128:131], v83 offset:7168
	global_load_lds_dwordx4 v[132:133], off
	v_lshl_add_u64 v[132:133], v[36:37], 0, s[10:11]
	s_add_i32 m0, s25, 0xe000
	s_nop 0
	global_load_lds_dwordx4 v[132:133], off
	s_waitcnt vmcnt(8)
	s_waitcnt lgkmcnt(0)
	s_barrier
	v_mfma_f32_16x16x32_bf16 v[74:77], v[84:87], v[100:103], v[74:77]
	v_mfma_f32_16x16x32_bf16 v[70:73], v[92:95], v[100:103], v[70:73]
	v_mfma_f32_16x16x32_bf16 v[66:69], v[84:87], v[108:111], v[66:69]
	v_mfma_f32_16x16x32_bf16 v[62:65], v[92:95], v[108:111], v[62:65]
	v_mfma_f32_16x16x32_bf16 v[58:61], v[84:87], v[116:119], v[58:61]
	v_mfma_f32_16x16x32_bf16 v[54:57], v[92:95], v[116:119], v[54:57]
	v_mfma_f32_16x16x32_bf16 v[50:53], v[84:87], v[124:127], v[50:53]
	v_mfma_f32_16x16x32_bf16 v[46:49], v[92:95], v[124:127], v[46:49]
	v_mfma_f32_16x16x32_bf16 v[74:77], v[88:91], v[104:107], v[74:77]
	v_mfma_f32_16x16x32_bf16 v[70:73], v[96:99], v[104:107], v[70:73]
	v_mfma_f32_16x16x32_bf16 v[66:69], v[88:91], v[112:115], v[66:69]
	v_mfma_f32_16x16x32_bf16 v[62:65], v[96:99], v[112:115], v[62:65]
	v_mfma_f32_16x16x32_bf16 v[58:61], v[88:91], v[120:123], v[58:61]
	v_mfma_f32_16x16x32_bf16 v[54:57], v[96:99], v[120:123], v[54:57]
	v_mfma_f32_16x16x32_bf16 v[50:53], v[88:91], v[128:131], v[50:53]
	v_mfma_f32_16x16x32_bf16 v[46:49], v[96:99], v[128:131], v[46:49]
	s_barrier
	s_add_i32 s46, s48, s24
	v_lshl_add_u64 v[132:133], s[12:13], 0, v[0:1]
	s_mov_b32 m0, s46
	ds_read_b128 v[100:103], v83 offset:16384
	ds_read_b128 v[104:107], v83 offset:17408
	ds_read_b128 v[108:111], v83 offset:18432
	ds_read_b128 v[112:115], v83 offset:19456
	ds_read_b128 v[116:119], v83 offset:20480
	ds_read_b128 v[120:123], v83 offset:21504
	ds_read_b128 v[124:127], v83 offset:22528
	ds_read_b128 v[128:131], v83 offset:23552
	global_load_lds_dwordx4 v[132:133], off
	s_add_i32 m0, s46, 0x2000
	s_add_u32 s46, s12, 0x100000
	v_lshl_add_u64 v[134:135], s[12:13], 0, v[34:35]
	s_addc_u32 s47, s13, 0
	global_load_lds_dwordx4 v[134:135], off
	v_lshl_add_u64 v[136:137], s[46:47], 0, v[0:1]
	s_mov_b32 m0, s26
	v_lshl_add_u64 v[138:139], s[14:15], 0, v[32:33]
	global_load_lds_dwordx4 v[136:137], off
	v_lshl_add_u64 v[136:137], s[46:47], 0, v[34:35]
	s_mov_b32 m0, s27
	s_nop 0
	global_load_lds_dwordx4 v[136:137], off
	v_lshl_add_u64 v[136:137], s[14:15], 0, v[30:31]
	s_mov_b32 m0, s25
	s_nop 0
	global_load_lds_dwordx4 v[136:137], off
	s_mov_b32 m0, s28
	s_nop 0
	global_load_lds_dwordx4 v[138:139], off
	s_waitcnt vmcnt(8)
	s_waitcnt lgkmcnt(0)
	s_barrier
	v_mfma_f32_16x16x32_bf16 v[42:45], v[84:87], v[100:103], v[42:45]
	v_mfma_f32_16x16x32_bf16 v[38:41], v[92:95], v[100:103], v[38:41]
	v_mfma_f32_16x16x32_bf16 v[26:29], v[84:87], v[108:111], v[26:29]
	v_mfma_f32_16x16x32_bf16 v[22:25], v[92:95], v[108:111], v[22:25]
	v_mfma_f32_16x16x32_bf16 v[18:21], v[84:87], v[116:119], v[18:21]
	v_mfma_f32_16x16x32_bf16 v[10:13], v[92:95], v[116:119], v[10:13]
	v_mfma_f32_16x16x32_bf16 v[6:9], v[84:87], v[124:127], v[6:9]
	v_mfma_f32_16x16x32_bf16 v[2:5], v[92:95], v[124:127], v[2:5]
	v_mfma_f32_16x16x32_bf16 v[42:45], v[88:91], v[104:107], v[42:45]
	v_mfma_f32_16x16x32_bf16 v[38:41], v[96:99], v[104:107], v[38:41]
	v_mfma_f32_16x16x32_bf16 v[26:29], v[88:91], v[112:115], v[26:29]
	v_mfma_f32_16x16x32_bf16 v[22:25], v[96:99], v[112:115], v[22:25]
	v_mfma_f32_16x16x32_bf16 v[18:21], v[88:91], v[120:123], v[18:21]
	v_mfma_f32_16x16x32_bf16 v[10:13], v[96:99], v[120:123], v[10:13]
	v_mfma_f32_16x16x32_bf16 v[6:9], v[88:91], v[128:131], v[6:9]
	v_mfma_f32_16x16x32_bf16 v[2:5], v[96:99], v[128:131], v[2:5]
	s_barrier
	s_add_i32 s46, 0, 0x18000
	v_add_u32_e32 v96, s46, v82
	ds_read_b128 v[84:87], v96
	ds_read_b128 v[88:91], v96 offset:1024
	ds_read_b128 v[92:95], v96 offset:2048
	ds_read_b128 v[96:99], v96 offset:3072
	s_add_u32 s14, s14, 0x80000
	s_addc_u32 s15, s15, 0
	s_mov_b32 m0, s29
	v_lshl_add_u64 v[140:141], s[14:15], 0, v[30:31]
	ds_read_b128 v[100:103], v83 offset:32768
	ds_read_b128 v[104:107], v83 offset:33792
	ds_read_b128 v[108:111], v83 offset:34816
	ds_read_b128 v[112:115], v83 offset:35840
	ds_read_b128 v[116:119], v83 offset:36864
	ds_read_b128 v[120:123], v83 offset:37888
	ds_read_b128 v[124:127], v83 offset:38912
	ds_read_b128 v[128:131], v83 offset:39936
	global_load_lds_dwordx4 v[140:141], off
	v_lshl_add_u64 v[140:141], s[14:15], 0, v[32:33]
	s_mov_b32 m0, s30
	s_nop 0
	global_load_lds_dwordx4 v[140:141], off
	s_waitcnt vmcnt(8)
	s_waitcnt lgkmcnt(0)
	s_barrier
	v_mfma_f32_16x16x32_bf16 v[74:77], v[84:87], v[100:103], v[74:77]
	v_mfma_f32_16x16x32_bf16 v[70:73], v[92:95], v[100:103], v[70:73]
	v_mfma_f32_16x16x32_bf16 v[66:69], v[84:87], v[108:111], v[66:69]
	v_mfma_f32_16x16x32_bf16 v[62:65], v[92:95], v[108:111], v[62:65]
	v_mfma_f32_16x16x32_bf16 v[58:61], v[84:87], v[116:119], v[58:61]
	v_mfma_f32_16x16x32_bf16 v[54:57], v[92:95], v[116:119], v[54:57]
	v_mfma_f32_16x16x32_bf16 v[50:53], v[84:87], v[124:127], v[50:53]
	v_mfma_f32_16x16x32_bf16 v[46:49], v[92:95], v[124:127], v[46:49]
	v_mfma_f32_16x16x32_bf16 v[74:77], v[88:91], v[104:107], v[74:77]
	v_mfma_f32_16x16x32_bf16 v[70:73], v[96:99], v[104:107], v[70:73]
	v_mfma_f32_16x16x32_bf16 v[66:69], v[88:91], v[112:115], v[66:69]
	v_mfma_f32_16x16x32_bf16 v[62:65], v[96:99], v[112:115], v[62:65]
	v_mfma_f32_16x16x32_bf16 v[58:61], v[88:91], v[120:123], v[58:61]
	v_mfma_f32_16x16x32_bf16 v[54:57], v[96:99], v[120:123], v[54:57]
	v_mfma_f32_16x16x32_bf16 v[50:53], v[88:91], v[128:131], v[50:53]
	v_mfma_f32_16x16x32_bf16 v[46:49], v[96:99], v[128:131], v[46:49]
	s_barrier
	s_add_i32 s14, s46, s24
	v_lshl_add_u64 v[132:133], v[132:133], 0, s[96:97]
	s_mov_b32 m0, s14
	ds_read_b128 v[100:103], v83 offset:49152
	ds_read_b128 v[104:107], v83 offset:50176
	ds_read_b128 v[108:111], v83 offset:51200
	ds_read_b128 v[112:115], v83 offset:52224
	ds_read_b128 v[116:119], v83 offset:53248
	ds_read_b128 v[120:123], v83 offset:54272
	ds_read_b128 v[124:127], v83 offset:55296
	ds_read_b128 v[128:131], v83 offset:56320
	global_load_lds_dwordx4 v[132:133], off
	s_add_i32 m0, s14, 0x2000
	s_add_u32 s12, s12, 0x100080
	v_lshl_add_u64 v[132:133], v[134:135], 0, s[96:97]
	s_addc_u32 s13, s13, 0
	global_load_lds_dwordx4 v[132:133], off
	v_lshl_add_u64 v[132:133], s[12:13], 0, v[0:1]
	s_mov_b32 m0, s37
	s_nop 0
	global_load_lds_dwordx4 v[132:133], off
	v_lshl_add_u64 v[132:133], s[12:13], 0, v[34:35]
	s_mov_b32 m0, s38
	s_nop 0
	global_load_lds_dwordx4 v[132:133], off
	v_lshl_add_u64 v[132:133], v[136:137], 0, s[96:97]
	s_mov_b32 m0, s34
	s_nop 0
	global_load_lds_dwordx4 v[132:133], off
	v_lshl_add_u64 v[132:133], v[138:139], 0, s[96:97]
	s_mov_b32 m0, s36
	s_nop 0
	global_load_lds_dwordx4 v[132:133], off
	s_waitcnt vmcnt(8)
	s_waitcnt lgkmcnt(0)
	s_barrier
	v_mfma_f32_16x16x32_bf16 v[42:45], v[84:87], v[100:103], v[42:45]
	v_mfma_f32_16x16x32_bf16 v[38:41], v[92:95], v[100:103], v[38:41]
	v_mfma_f32_16x16x32_bf16 v[26:29], v[84:87], v[108:111], v[26:29]
	v_mfma_f32_16x16x32_bf16 v[22:25], v[92:95], v[108:111], v[22:25]
	v_mfma_f32_16x16x32_bf16 v[18:21], v[84:87], v[116:119], v[18:21]
	v_mfma_f32_16x16x32_bf16 v[10:13], v[92:95], v[116:119], v[10:13]
	v_mfma_f32_16x16x32_bf16 v[6:9], v[84:87], v[124:127], v[6:9]
	v_mfma_f32_16x16x32_bf16 v[2:5], v[92:95], v[124:127], v[2:5]
	v_mfma_f32_16x16x32_bf16 v[42:45], v[88:91], v[104:107], v[42:45]
	v_mfma_f32_16x16x32_bf16 v[38:41], v[96:99], v[104:107], v[38:41]
	v_mfma_f32_16x16x32_bf16 v[26:29], v[88:91], v[112:115], v[26:29]
	v_mfma_f32_16x16x32_bf16 v[22:25], v[96:99], v[112:115], v[22:25]
	v_mfma_f32_16x16x32_bf16 v[18:21], v[88:91], v[120:123], v[18:21]
	v_mfma_f32_16x16x32_bf16 v[10:13], v[96:99], v[120:123], v[10:13]
	v_mfma_f32_16x16x32_bf16 v[6:9], v[88:91], v[128:131], v[6:9]
	v_mfma_f32_16x16x32_bf16 v[2:5], v[96:99], v[128:131], v[2:5]
	s_barrier
	s_add_i32 s45, s45, 2
	s_add_u32 s10, s10, 0x100
	s_addc_u32 s11, s11, 0
	s_cmp_gt_u32 s45, 61
	s_cbranch_scc0 .LBB0_1300
	s_cmpk_lt_u32 s22, 0x100
	s_cbranch_scc0 .LBB0_1303
	s_barrier

.LBB0_1321:
	s_add_u32 s36, s2, 0xfffc0080
	s_addc_u32 s37, s3, -1
	s_add_i32 s40, 0, 0x10000
	s_cmp_eq_u32 s34, 4
	s_cselect_b32 s39, s29, s37
	s_cselect_b32 s38, s28, s36
	v_add_u32_e32 v0, s40, v141
	s_cselect_b32 s37, s5, s27
	s_cselect_b32 s36, s7, s25
	s_add_i32 s58, 0, 0x14000
	ds_read_b128 v[148:151], v0
	ds_read_b128 v[152:155], v0 offset:1024
	ds_read_b128 v[156:159], v0 offset:2048
	ds_read_b128 v[160:163], v0 offset:3072
	v_add_u32_e32 v0, s58, v141
	ds_read_b128 v[164:167], v0
	ds_read_b128 v[168:171], v0 offset:1024
	ds_read_b128 v[172:175], v0 offset:2048
	ds_read_b128 v[176:179], v0 offset:3072
	s_add_i32 m0, s49, 0xc000
	ds_read_b128 v[180:183], v186
	ds_read_b128 v[188:191], v186 offset:1024
	ds_read_b128 v[192:195], v186 offset:2048
	ds_read_b128 v[204:207], v186 offset:3072
	ds_read_b128 v[208:211], v186 offset:4096
	ds_read_b128 v[212:215], v186 offset:5120
	ds_read_b128 v[216:219], v186 offset:6144
	ds_read_b128 v[220:223], v186 offset:7168
	global_load_lds_dwordx4 v146, s[2:3]
	s_add_i32 m0, s49, 0xe000
	s_nop 0
	global_load_lds_dwordx4 v144, s[2:3]
	s_waitcnt vmcnt(8)
	s_waitcnt lgkmcnt(0)
	s_barrier
	v_mfma_f32_16x16x32_bf16 v[130:133], v[148:151], v[180:183], v[130:133]
	v_mfma_f32_16x16x32_bf16 v[126:129], v[156:159], v[180:183], v[126:129]
	v_mfma_f32_16x16x32_bf16 v[114:117], v[148:151], v[192:195], v[114:117]
	v_mfma_f32_16x16x32_bf16 v[110:113], v[156:159], v[192:195], v[110:113]
	v_mfma_f32_16x16x32_bf16 v[98:101], v[148:151], v[208:211], v[98:101]
	v_mfma_f32_16x16x32_bf16 v[94:97], v[156:159], v[208:211], v[94:97]
	v_mfma_f32_16x16x32_bf16 v[82:85], v[148:151], v[216:219], v[82:85]
	v_mfma_f32_16x16x32_bf16 v[78:81], v[156:159], v[216:219], v[78:81]
	v_mfma_f32_16x16x32_bf16 v[130:133], v[152:155], v[188:191], v[130:133]
	v_mfma_f32_16x16x32_bf16 v[126:129], v[160:163], v[188:191], v[126:129]
	v_mfma_f32_16x16x32_bf16 v[114:117], v[152:155], v[204:207], v[114:117]
	v_mfma_f32_16x16x32_bf16 v[110:113], v[160:163], v[204:207], v[110:113]
	v_mfma_f32_16x16x32_bf16 v[98:101], v[152:155], v[212:215], v[98:101]
	v_mfma_f32_16x16x32_bf16 v[94:97], v[160:163], v[212:215], v[94:97]
	v_mfma_f32_16x16x32_bf16 v[82:85], v[152:155], v[220:223], v[82:85]
	v_mfma_f32_16x16x32_bf16 v[78:81], v[160:163], v[220:223], v[78:81]
	v_mfma_f32_16x16x32_bf16 v[122:125], v[164:167], v[180:183], v[122:125]
	v_mfma_f32_16x16x32_bf16 v[118:121], v[172:175], v[180:183], v[118:121]
	v_mfma_f32_16x16x32_bf16 v[106:109], v[164:167], v[192:195], v[106:109]
	v_mfma_f32_16x16x32_bf16 v[102:105], v[172:175], v[192:195], v[102:105]
	v_mfma_f32_16x16x32_bf16 v[90:93], v[164:167], v[208:211], v[90:93]
	v_mfma_f32_16x16x32_bf16 v[86:89], v[172:175], v[208:211], v[86:89]
	v_mfma_f32_16x16x32_bf16 v[74:77], v[164:167], v[216:219], v[74:77]
	v_mfma_f32_16x16x32_bf16 v[70:73], v[172:175], v[216:219], v[70:73]
	v_mfma_f32_16x16x32_bf16 v[122:125], v[168:171], v[188:191], v[122:125]
	v_mfma_f32_16x16x32_bf16 v[118:121], v[176:179], v[188:191], v[118:121]
	v_mfma_f32_16x16x32_bf16 v[106:109], v[168:171], v[204:207], v[106:109]
	v_mfma_f32_16x16x32_bf16 v[102:105], v[176:179], v[204:207], v[102:105]
	v_mfma_f32_16x16x32_bf16 v[90:93], v[168:171], v[212:215], v[90:93]
	v_mfma_f32_16x16x32_bf16 v[86:89], v[176:179], v[212:215], v[86:89]
	v_mfma_f32_16x16x32_bf16 v[74:77], v[168:171], v[220:223], v[74:77]
	v_mfma_f32_16x16x32_bf16 v[70:73], v[176:179], v[220:223], v[70:73]
	s_barrier
	s_add_i32 s40, s40, s48
	s_mov_b32 m0, s40
	ds_read_b128 v[180:183], v186 offset:16384
	ds_read_b128 v[188:191], v186 offset:17408
	ds_read_b128 v[192:195], v186 offset:18432
	ds_read_b128 v[204:207], v186 offset:19456
	ds_read_b128 v[208:211], v186 offset:20480
	ds_read_b128 v[212:215], v186 offset:21504
	ds_read_b128 v[216:219], v186 offset:22528
	ds_read_b128 v[220:223], v186 offset:23552
	global_load_lds_dwordx4 v134, s[36:37]
	s_add_i32 m0, s40, 0x2000
	s_add_u32 s56, s36, 0x20000
	s_addc_u32 s57, s37, 0
	s_add_i32 s40, s58, s48
	global_load_lds_dwordx4 v138, s[36:37]
	s_mov_b32 m0, s40
	s_add_u32 s90, s38, s96
	s_addc_u32 s91, s39, s97
	global_load_lds_dwordx4 v134, s[56:57]
	s_add_i32 m0, s40, 0x2000
	s_nop 0
	global_load_lds_dwordx4 v138, s[56:57]
	s_mov_b32 m0, s49
	s_nop 0
	global_load_lds_dwordx4 v14, s[38:39]
	s_mov_b32 m0, s50
	s_nop 0
	global_load_lds_dwordx4 v136, s[38:39]
	s_waitcnt vmcnt(8)
	s_waitcnt lgkmcnt(0)
	s_barrier
	v_mfma_f32_16x16x32_bf16 v[66:69], v[148:151], v[180:183], v[66:69]
	v_mfma_f32_16x16x32_bf16 v[62:65], v[156:159], v[180:183], v[62:65]
	v_mfma_f32_16x16x32_bf16 v[50:53], v[148:151], v[192:195], v[50:53]
	v_mfma_f32_16x16x32_bf16 v[46:49], v[156:159], v[192:195], v[46:49]
	v_mfma_f32_16x16x32_bf16 v[34:37], v[148:151], v[208:211], v[34:37]
	v_mfma_f32_16x16x32_bf16 v[30:33], v[156:159], v[208:211], v[30:33]
	v_mfma_f32_16x16x32_bf16 v[18:21], v[148:151], v[216:219], v[18:21]
	v_mfma_f32_16x16x32_bf16 v[10:13], v[156:159], v[216:219], v[10:13]
	v_mfma_f32_16x16x32_bf16 v[66:69], v[152:155], v[188:191], v[66:69]
	v_mfma_f32_16x16x32_bf16 v[62:65], v[160:163], v[188:191], v[62:65]
	v_mfma_f32_16x16x32_bf16 v[50:53], v[152:155], v[204:207], v[50:53]
	v_mfma_f32_16x16x32_bf16 v[46:49], v[160:163], v[204:207], v[46:49]
	v_mfma_f32_16x16x32_bf16 v[34:37], v[152:155], v[212:215], v[34:37]
	v_mfma_f32_16x16x32_bf16 v[30:33], v[160:163], v[212:215], v[30:33]
	v_mfma_f32_16x16x32_bf16 v[18:21], v[152:155], v[220:223], v[18:21]
	v_mfma_f32_16x16x32_bf16 v[10:13], v[160:163], v[220:223], v[10:13]
	v_mfma_f32_16x16x32_bf16 v[58:61], v[164:167], v[180:183], v[58:61]
	v_mfma_f32_16x16x32_bf16 v[54:57], v[172:175], v[180:183], v[54:57]
	v_mfma_f32_16x16x32_bf16 v[42:45], v[164:167], v[192:195], v[42:45]
	v_mfma_f32_16x16x32_bf16 v[38:41], v[172:175], v[192:195], v[38:41]
	v_mfma_f32_16x16x32_bf16 v[26:29], v[164:167], v[208:211], v[26:29]
	v_mfma_f32_16x16x32_bf16 v[22:25], v[172:175], v[208:211], v[22:25]
	v_mfma_f32_16x16x32_bf16 v[6:9], v[164:167], v[216:219], v[6:9]
	v_mfma_f32_16x16x32_bf16 v[2:5], v[172:175], v[216:219], v[2:5]
	v_mfma_f32_16x16x32_bf16 v[58:61], v[168:171], v[188:191], v[58:61]
	v_mfma_f32_16x16x32_bf16 v[54:57], v[176:179], v[188:191], v[54:57]
	v_mfma_f32_16x16x32_bf16 v[42:45], v[168:171], v[204:207], v[42:45]
	v_mfma_f32_16x16x32_bf16 v[38:41], v[176:179], v[204:207], v[38:41]
	v_mfma_f32_16x16x32_bf16 v[26:29], v[168:171], v[212:215], v[26:29]
	v_mfma_f32_16x16x32_bf16 v[22:25], v[176:179], v[212:215], v[22:25]
	v_mfma_f32_16x16x32_bf16 v[6:9], v[168:171], v[220:223], v[6:9]
	v_mfma_f32_16x16x32_bf16 v[2:5], v[176:179], v[220:223], v[2:5]
	s_barrier
	s_add_i32 s40, 0, 0x18000
	v_add_u32_e32 v0, s40, v141
	s_add_i32 s56, 0, 0x1c000
	ds_read_b128 v[148:151], v0
	ds_read_b128 v[152:155], v0 offset:1024
	ds_read_b128 v[156:159], v0 offset:2048
	ds_read_b128 v[160:163], v0 offset:3072
	v_add_u32_e32 v0, s56, v141
	ds_read_b128 v[164:167], v0
	ds_read_b128 v[168:171], v0 offset:1024
	ds_read_b128 v[172:175], v0 offset:2048
	ds_read_b128 v[176:179], v0 offset:3072
	s_add_u32 s38, s38, 0x40000
	s_addc_u32 s39, s39, 0
	s_mov_b32 m0, s51
	ds_read_b128 v[180:183], v186 offset:32768
	ds_read_b128 v[188:191], v186 offset:33792
	ds_read_b128 v[192:195], v186 offset:34816
	ds_read_b128 v[204:207], v186 offset:35840
	ds_read_b128 v[208:211], v186 offset:36864
	ds_read_b128 v[212:215], v186 offset:37888
	ds_read_b128 v[216:219], v186 offset:38912
	ds_read_b128 v[220:223], v186 offset:39936
	global_load_lds_dwordx4 v14, s[38:39]
	s_mov_b32 m0, s52
	s_nop 0
	global_load_lds_dwordx4 v136, s[38:39]
	s_waitcnt vmcnt(8)
	s_waitcnt lgkmcnt(0)
	s_barrier
	v_mfma_f32_16x16x32_bf16 v[130:133], v[148:151], v[180:183], v[130:133]
	v_mfma_f32_16x16x32_bf16 v[126:129], v[156:159], v[180:183], v[126:129]
	v_mfma_f32_16x16x32_bf16 v[114:117], v[148:151], v[192:195], v[114:117]
	v_mfma_f32_16x16x32_bf16 v[110:113], v[156:159], v[192:195], v[110:113]
	v_mfma_f32_16x16x32_bf16 v[98:101], v[148:151], v[208:211], v[98:101]
	v_mfma_f32_16x16x32_bf16 v[94:97], v[156:159], v[208:211], v[94:97]
	v_mfma_f32_16x16x32_bf16 v[82:85], v[148:151], v[216:219], v[82:85]
	v_mfma_f32_16x16x32_bf16 v[78:81], v[156:159], v[216:219], v[78:81]
	v_mfma_f32_16x16x32_bf16 v[130:133], v[152:155], v[188:191], v[130:133]
	v_mfma_f32_16x16x32_bf16 v[126:129], v[160:163], v[188:191], v[126:129]
	v_mfma_f32_16x16x32_bf16 v[114:117], v[152:155], v[204:207], v[114:117]
	v_mfma_f32_16x16x32_bf16 v[110:113], v[160:163], v[204:207], v[110:113]
	v_mfma_f32_16x16x32_bf16 v[98:101], v[152:155], v[212:215], v[98:101]
	v_mfma_f32_16x16x32_bf16 v[94:97], v[160:163], v[212:215], v[94:97]
	v_mfma_f32_16x16x32_bf16 v[82:85], v[152:155], v[220:223], v[82:85]
	v_mfma_f32_16x16x32_bf16 v[78:81], v[160:163], v[220:223], v[78:81]
	v_mfma_f32_16x16x32_bf16 v[122:125], v[164:167], v[180:183], v[122:125]
	v_mfma_f32_16x16x32_bf16 v[118:121], v[172:175], v[180:183], v[118:121]
	v_mfma_f32_16x16x32_bf16 v[106:109], v[164:167], v[192:195], v[106:109]
	v_mfma_f32_16x16x32_bf16 v[102:105], v[172:175], v[192:195], v[102:105]
	v_mfma_f32_16x16x32_bf16 v[90:93], v[164:167], v[208:211], v[90:93]
	v_mfma_f32_16x16x32_bf16 v[86:89], v[172:175], v[208:211], v[86:89]
	v_mfma_f32_16x16x32_bf16 v[74:77], v[164:167], v[216:219], v[74:77]
	v_mfma_f32_16x16x32_bf16 v[70:73], v[172:175], v[216:219], v[70:73]
	v_mfma_f32_16x16x32_bf16 v[122:125], v[168:171], v[188:191], v[122:125]
	v_mfma_f32_16x16x32_bf16 v[118:121], v[176:179], v[188:191], v[118:121]
	v_mfma_f32_16x16x32_bf16 v[106:109], v[168:171], v[204:207], v[106:109]
	v_mfma_f32_16x16x32_bf16 v[102:105], v[176:179], v[204:207], v[102:105]
	v_mfma_f32_16x16x32_bf16 v[90:93], v[168:171], v[212:215], v[90:93]
	v_mfma_f32_16x16x32_bf16 v[86:89], v[176:179], v[212:215], v[86:89]
	v_mfma_f32_16x16x32_bf16 v[74:77], v[168:171], v[220:223], v[74:77]
	v_mfma_f32_16x16x32_bf16 v[70:73], v[176:179], v[220:223], v[70:73]
	s_barrier
	s_add_i32 s38, s40, s48
	s_add_u32 s88, s36, s96
	s_addc_u32 s89, s37, s97
	s_mov_b32 m0, s38
	ds_read_b128 v[180:183], v186 offset:49152
	ds_read_b128 v[188:191], v186 offset:50176
	ds_read_b128 v[192:195], v186 offset:51200
	ds_read_b128 v[204:207], v186 offset:52224
	ds_read_b128 v[208:211], v186 offset:53248
	ds_read_b128 v[212:215], v186 offset:54272
	ds_read_b128 v[216:219], v186 offset:55296
	ds_read_b128 v[220:223], v186 offset:56320
	global_load_lds_dwordx4 v134, s[88:89]
	s_add_i32 m0, s38, 0x2000
	s_add_u32 s36, s36, 0x20080
	s_addc_u32 s37, s37, 0
	s_add_i32 s38, s56, s48
	global_load_lds_dwordx4 v138, s[88:89]
	s_mov_b32 m0, s38
	s_nop 0
	global_load_lds_dwordx4 v134, s[36:37]
	s_add_i32 m0, s38, 0x2000
	s_nop 0
	global_load_lds_dwordx4 v138, s[36:37]
	s_mov_b32 m0, s53
	s_nop 0
	global_load_lds_dwordx4 v14, s[90:91]
	s_mov_b32 m0, s54
	s_nop 0
	global_load_lds_dwordx4 v136, s[90:91]
	s_waitcnt vmcnt(8)
	s_waitcnt lgkmcnt(0)
	s_barrier
	v_mfma_f32_16x16x32_bf16 v[66:69], v[148:151], v[180:183], v[66:69]
	v_mfma_f32_16x16x32_bf16 v[62:65], v[156:159], v[180:183], v[62:65]
	v_mfma_f32_16x16x32_bf16 v[50:53], v[148:151], v[192:195], v[50:53]
	v_mfma_f32_16x16x32_bf16 v[46:49], v[156:159], v[192:195], v[46:49]
	v_mfma_f32_16x16x32_bf16 v[34:37], v[148:151], v[208:211], v[34:37]
	v_mfma_f32_16x16x32_bf16 v[30:33], v[156:159], v[208:211], v[30:33]
	v_mfma_f32_16x16x32_bf16 v[18:21], v[148:151], v[216:219], v[18:21]
	v_mfma_f32_16x16x32_bf16 v[10:13], v[156:159], v[216:219], v[10:13]
	v_mfma_f32_16x16x32_bf16 v[66:69], v[152:155], v[188:191], v[66:69]
	v_mfma_f32_16x16x32_bf16 v[62:65], v[160:163], v[188:191], v[62:65]
	v_mfma_f32_16x16x32_bf16 v[50:53], v[152:155], v[204:207], v[50:53]
	v_mfma_f32_16x16x32_bf16 v[46:49], v[160:163], v[204:207], v[46:49]
	v_mfma_f32_16x16x32_bf16 v[34:37], v[152:155], v[212:215], v[34:37]
	v_mfma_f32_16x16x32_bf16 v[30:33], v[160:163], v[212:215], v[30:33]
	v_mfma_f32_16x16x32_bf16 v[18:21], v[152:155], v[220:223], v[18:21]
	v_mfma_f32_16x16x32_bf16 v[10:13], v[160:163], v[220:223], v[10:13]
	v_mfma_f32_16x16x32_bf16 v[58:61], v[164:167], v[180:183], v[58:61]
	v_mfma_f32_16x16x32_bf16 v[54:57], v[172:175], v[180:183], v[54:57]
	v_mfma_f32_16x16x32_bf16 v[42:45], v[164:167], v[192:195], v[42:45]
	v_mfma_f32_16x16x32_bf16 v[38:41], v[172:175], v[192:195], v[38:41]
	v_mfma_f32_16x16x32_bf16 v[26:29], v[164:167], v[208:211], v[26:29]
	v_mfma_f32_16x16x32_bf16 v[22:25], v[172:175], v[208:211], v[22:25]
	v_mfma_f32_16x16x32_bf16 v[6:9], v[164:167], v[216:219], v[6:9]
	v_mfma_f32_16x16x32_bf16 v[2:5], v[172:175], v[216:219], v[2:5]
	v_mfma_f32_16x16x32_bf16 v[58:61], v[168:171], v[188:191], v[58:61]
	v_mfma_f32_16x16x32_bf16 v[54:57], v[176:179], v[188:191], v[54:57]
	v_mfma_f32_16x16x32_bf16 v[42:45], v[168:171], v[204:207], v[42:45]
	v_mfma_f32_16x16x32_bf16 v[38:41], v[176:179], v[204:207], v[38:41]
	v_mfma_f32_16x16x32_bf16 v[26:29], v[168:171], v[212:215], v[26:29]
	v_mfma_f32_16x16x32_bf16 v[22:25], v[176:179], v[212:215], v[22:25]
	v_mfma_f32_16x16x32_bf16 v[6:9], v[168:171], v[220:223], v[6:9]
	v_mfma_f32_16x16x32_bf16 v[2:5], v[176:179], v[220:223], v[2:5]
	s_barrier
	s_add_i32 s34, s34, 2
	s_add_u32 s25, s25, 0x100
	s_addc_u32 s27, s27, 0
	s_add_u32 s2, s2, 0x100
	s_addc_u32 s3, s3, 0
	s_cmp_gt_u32 s34, 5
	s_cbranch_scc0 .LBB0_1321
	s_and_b64 vcc, exec, s[22:23]
	s_cbranch_vccz .LBB0_1324
	s_barrier

.LBB0_2399:
	s_add_u32 s90, s22, s40
	s_addc_u32 s91, s23, s41
	s_add_u32 s90, s90, 0x80080
	s_addc_u32 s91, s91, 0
	s_add_u32 s44, s22, s40
	s_addc_u32 s45, s23, s41
	s_add_u32 s44, s44, 0x100
	s_addc_u32 s45, s45, 0
	s_add_u32 s67, s63, s40
	s_addc_u32 s68, s64, s41
	s_add_i32 s69, 0, 0x10000
	s_cmpk_eq_i32 s40, 0xf00
	s_cselect_b32 s47, s25, s45
	s_cselect_b32 s46, s34, s44
	s_cselect_b32 s45, s27, s68
	s_cselect_b32 s44, s65, s67
	s_add_i32 s67, 0, 0x14000
	v_add_u32_e32 v154, s69, v180
	v_add_u32_e32 v170, s67, v180
	ds_read_b128 v[142:145], v154
	ds_read_b128 v[146:149], v154 offset:1024
	ds_read_b128 v[150:153], v154 offset:2048
	ds_read_b128 v[154:157], v154 offset:3072
	ds_read_b128 v[158:161], v170
	ds_read_b128 v[162:165], v170 offset:1024
	ds_read_b128 v[166:169], v170 offset:2048
	ds_read_b128 v[170:173], v170 offset:3072
	s_add_i32 m0, s5, 0xc000
	ds_read_b128 v[174:177], v184
	ds_read_b128 v[186:189], v184 offset:1024
	ds_read_b128 v[190:193], v184 offset:2048
	ds_read_b128 v[194:197], v184 offset:3072
	ds_read_b128 v[200:203], v184 offset:4096
	ds_read_b128 v[204:207], v184 offset:5120
	ds_read_b128 v[208:211], v184 offset:6144
	ds_read_b128 v[212:215], v184 offset:7168
	global_load_lds_dwordx4 v136, s[90:91]
	s_add_i32 m0, s5, 0xe000
	s_nop 0
	global_load_lds_dwordx4 v134, s[90:91]
	s_waitcnt vmcnt(8)
	s_waitcnt lgkmcnt(0)
	s_barrier
	v_mfma_f32_16x16x32_bf16 v[130:133], v[142:145], v[174:177], v[130:133]
	v_mfma_f32_16x16x32_bf16 v[126:129], v[150:153], v[174:177], v[126:129]
	v_mfma_f32_16x16x32_bf16 v[122:125], v[142:145], v[190:193], v[122:125]
	v_mfma_f32_16x16x32_bf16 v[118:121], v[150:153], v[190:193], v[118:121]
	v_mfma_f32_16x16x32_bf16 v[114:117], v[142:145], v[200:203], v[114:117]
	v_mfma_f32_16x16x32_bf16 v[110:113], v[150:153], v[200:203], v[110:113]
	v_mfma_f32_16x16x32_bf16 v[106:109], v[142:145], v[208:211], v[106:109]
	v_mfma_f32_16x16x32_bf16 v[102:105], v[150:153], v[208:211], v[102:105]
	v_mfma_f32_16x16x32_bf16 v[130:133], v[146:149], v[186:189], v[130:133]
	v_mfma_f32_16x16x32_bf16 v[126:129], v[154:157], v[186:189], v[126:129]
	v_mfma_f32_16x16x32_bf16 v[122:125], v[146:149], v[194:197], v[122:125]
	v_mfma_f32_16x16x32_bf16 v[118:121], v[154:157], v[194:197], v[118:121]
	v_mfma_f32_16x16x32_bf16 v[114:117], v[146:149], v[204:207], v[114:117]
	v_mfma_f32_16x16x32_bf16 v[110:113], v[154:157], v[204:207], v[110:113]
	v_mfma_f32_16x16x32_bf16 v[106:109], v[146:149], v[212:215], v[106:109]
	v_mfma_f32_16x16x32_bf16 v[102:105], v[154:157], v[212:215], v[102:105]
	v_mfma_f32_16x16x32_bf16 v[98:101], v[158:161], v[174:177], v[98:101]
	v_mfma_f32_16x16x32_bf16 v[94:97], v[166:169], v[174:177], v[94:97]
	v_mfma_f32_16x16x32_bf16 v[90:93], v[158:161], v[190:193], v[90:93]
	v_mfma_f32_16x16x32_bf16 v[86:89], v[166:169], v[190:193], v[86:89]
	v_mfma_f32_16x16x32_bf16 v[82:85], v[158:161], v[200:203], v[82:85]
	v_mfma_f32_16x16x32_bf16 v[78:81], v[166:169], v[200:203], v[78:81]
	v_mfma_f32_16x16x32_bf16 v[74:77], v[158:161], v[208:211], v[74:77]
	v_mfma_f32_16x16x32_bf16 v[70:73], v[166:169], v[208:211], v[70:73]
	v_mfma_f32_16x16x32_bf16 v[98:101], v[162:165], v[186:189], v[98:101]
	v_mfma_f32_16x16x32_bf16 v[94:97], v[170:173], v[186:189], v[94:97]
	v_mfma_f32_16x16x32_bf16 v[90:93], v[162:165], v[194:197], v[90:93]
	v_mfma_f32_16x16x32_bf16 v[86:89], v[170:173], v[194:197], v[86:89]
	v_mfma_f32_16x16x32_bf16 v[82:85], v[162:165], v[204:207], v[82:85]
	v_mfma_f32_16x16x32_bf16 v[78:81], v[170:173], v[204:207], v[78:81]
	v_mfma_f32_16x16x32_bf16 v[74:77], v[162:165], v[212:215], v[74:77]
	v_mfma_f32_16x16x32_bf16 v[70:73], v[170:173], v[212:215], v[70:73]
	s_barrier
	s_add_i32 s68, s69, s53
	s_mov_b32 m0, s68
	ds_read_b128 v[174:177], v184 offset:16384
	ds_read_b128 v[186:189], v184 offset:17408
	ds_read_b128 v[190:193], v184 offset:18432
	ds_read_b128 v[194:197], v184 offset:19456
	ds_read_b128 v[200:203], v184 offset:20480
	ds_read_b128 v[204:207], v184 offset:21504
	ds_read_b128 v[208:211], v184 offset:22528
	ds_read_b128 v[212:215], v184 offset:23552
	global_load_lds_dwordx4 v0, s[44:45]
	s_add_i32 m0, s68, 0x2000
	s_add_u32 s68, s44, 0x80000
	s_addc_u32 s69, s45, 0
	s_add_i32 s67, s67, s53
	global_load_lds_dwordx4 v14, s[44:45]
	s_mov_b32 m0, s67
	s_add_u32 s92, s46, s96
	s_addc_u32 s93, s47, s97
	global_load_lds_dwordx4 v0, s[68:69]
	s_add_i32 m0, s67, 0x2000
	s_nop 0
	global_load_lds_dwordx4 v14, s[68:69]
	s_mov_b32 m0, s5
	s_nop 0
	global_load_lds_dwordx4 v0, s[46:47]
	s_mov_b32 m0, s7
	s_nop 0
	global_load_lds_dwordx4 v14, s[46:47]
	s_waitcnt vmcnt(8)
	s_waitcnt lgkmcnt(0)
	s_barrier
	v_mfma_f32_16x16x32_bf16 v[66:69], v[142:145], v[174:177], v[66:69]
	v_mfma_f32_16x16x32_bf16 v[62:65], v[150:153], v[174:177], v[62:65]
	v_mfma_f32_16x16x32_bf16 v[58:61], v[142:145], v[190:193], v[58:61]
	v_mfma_f32_16x16x32_bf16 v[54:57], v[150:153], v[190:193], v[54:57]
	v_mfma_f32_16x16x32_bf16 v[50:53], v[142:145], v[200:203], v[50:53]
	v_mfma_f32_16x16x32_bf16 v[46:49], v[150:153], v[200:203], v[46:49]
	v_mfma_f32_16x16x32_bf16 v[42:45], v[142:145], v[208:211], v[42:45]
	v_mfma_f32_16x16x32_bf16 v[38:41], v[150:153], v[208:211], v[38:41]
	v_mfma_f32_16x16x32_bf16 v[66:69], v[146:149], v[186:189], v[66:69]
	v_mfma_f32_16x16x32_bf16 v[62:65], v[154:157], v[186:189], v[62:65]
	v_mfma_f32_16x16x32_bf16 v[58:61], v[146:149], v[194:197], v[58:61]
	v_mfma_f32_16x16x32_bf16 v[54:57], v[154:157], v[194:197], v[54:57]
	v_mfma_f32_16x16x32_bf16 v[50:53], v[146:149], v[204:207], v[50:53]
	v_mfma_f32_16x16x32_bf16 v[46:49], v[154:157], v[204:207], v[46:49]
	v_mfma_f32_16x16x32_bf16 v[42:45], v[146:149], v[212:215], v[42:45]
	v_mfma_f32_16x16x32_bf16 v[38:41], v[154:157], v[212:215], v[38:41]
	v_mfma_f32_16x16x32_bf16 v[34:37], v[158:161], v[174:177], v[34:37]
	v_mfma_f32_16x16x32_bf16 v[30:33], v[166:169], v[174:177], v[30:33]
	v_mfma_f32_16x16x32_bf16 v[26:29], v[158:161], v[190:193], v[26:29]
	v_mfma_f32_16x16x32_bf16 v[22:25], v[166:169], v[190:193], v[22:25]
	v_mfma_f32_16x16x32_bf16 v[18:21], v[158:161], v[200:203], v[18:21]
	v_mfma_f32_16x16x32_bf16 v[10:13], v[166:169], v[200:203], v[10:13]
	v_mfma_f32_16x16x32_bf16 v[6:9], v[158:161], v[208:211], v[6:9]
	v_mfma_f32_16x16x32_bf16 v[2:5], v[166:169], v[208:211], v[2:5]
	v_mfma_f32_16x16x32_bf16 v[34:37], v[162:165], v[186:189], v[34:37]
	v_mfma_f32_16x16x32_bf16 v[30:33], v[170:173], v[186:189], v[30:33]
	v_mfma_f32_16x16x32_bf16 v[26:29], v[162:165], v[194:197], v[26:29]
	v_mfma_f32_16x16x32_bf16 v[22:25], v[170:173], v[194:197], v[22:25]
	v_mfma_f32_16x16x32_bf16 v[18:21], v[162:165], v[204:207], v[18:21]
	v_mfma_f32_16x16x32_bf16 v[10:13], v[170:173], v[204:207], v[10:13]
	v_mfma_f32_16x16x32_bf16 v[6:9], v[162:165], v[212:215], v[6:9]
	v_mfma_f32_16x16x32_bf16 v[2:5], v[170:173], v[212:215], v[2:5]
	s_barrier
	s_add_i32 s67, 0, 0x18000
	s_add_i32 s68, 0, 0x1c000
	v_add_u32_e32 v154, s67, v180
	v_add_u32_e32 v170, s68, v180
	ds_read_b128 v[142:145], v154
	ds_read_b128 v[146:149], v154 offset:1024
	ds_read_b128 v[150:153], v154 offset:2048
	ds_read_b128 v[154:157], v154 offset:3072
	ds_read_b128 v[158:161], v170
	ds_read_b128 v[162:165], v170 offset:1024
	ds_read_b128 v[166:169], v170 offset:2048
	ds_read_b128 v[170:173], v170 offset:3072
	s_add_u32 s46, s46, 0x80000
	s_addc_u32 s47, s47, 0
	s_mov_b32 m0, s54
	ds_read_b128 v[174:177], v184 offset:32768
	ds_read_b128 v[186:189], v184 offset:33792
	ds_read_b128 v[190:193], v184 offset:34816
	ds_read_b128 v[194:197], v184 offset:35840
	ds_read_b128 v[200:203], v184 offset:36864
	ds_read_b128 v[204:207], v184 offset:37888
	ds_read_b128 v[208:211], v184 offset:38912
	ds_read_b128 v[212:215], v184 offset:39936
	global_load_lds_dwordx4 v0, s[46:47]
	s_mov_b32 m0, s55
	s_nop 0
	global_load_lds_dwordx4 v14, s[46:47]
	s_waitcnt vmcnt(8)
	s_waitcnt lgkmcnt(0)
	s_barrier
	v_mfma_f32_16x16x32_bf16 v[130:133], v[142:145], v[174:177], v[130:133]
	v_mfma_f32_16x16x32_bf16 v[126:129], v[150:153], v[174:177], v[126:129]
	v_mfma_f32_16x16x32_bf16 v[122:125], v[142:145], v[190:193], v[122:125]
	v_mfma_f32_16x16x32_bf16 v[118:121], v[150:153], v[190:193], v[118:121]
	v_mfma_f32_16x16x32_bf16 v[114:117], v[142:145], v[200:203], v[114:117]
	v_mfma_f32_16x16x32_bf16 v[110:113], v[150:153], v[200:203], v[110:113]
	v_mfma_f32_16x16x32_bf16 v[106:109], v[142:145], v[208:211], v[106:109]
	v_mfma_f32_16x16x32_bf16 v[102:105], v[150:153], v[208:211], v[102:105]
	v_mfma_f32_16x16x32_bf16 v[130:133], v[146:149], v[186:189], v[130:133]
	v_mfma_f32_16x16x32_bf16 v[126:129], v[154:157], v[186:189], v[126:129]
	v_mfma_f32_16x16x32_bf16 v[122:125], v[146:149], v[194:197], v[122:125]
	v_mfma_f32_16x16x32_bf16 v[118:121], v[154:157], v[194:197], v[118:121]
	v_mfma_f32_16x16x32_bf16 v[114:117], v[146:149], v[204:207], v[114:117]
	v_mfma_f32_16x16x32_bf16 v[110:113], v[154:157], v[204:207], v[110:113]
	v_mfma_f32_16x16x32_bf16 v[106:109], v[146:149], v[212:215], v[106:109]
	v_mfma_f32_16x16x32_bf16 v[102:105], v[154:157], v[212:215], v[102:105]
	v_mfma_f32_16x16x32_bf16 v[98:101], v[158:161], v[174:177], v[98:101]
	v_mfma_f32_16x16x32_bf16 v[94:97], v[166:169], v[174:177], v[94:97]
	v_mfma_f32_16x16x32_bf16 v[90:93], v[158:161], v[190:193], v[90:93]
	v_mfma_f32_16x16x32_bf16 v[86:89], v[166:169], v[190:193], v[86:89]
	v_mfma_f32_16x16x32_bf16 v[82:85], v[158:161], v[200:203], v[82:85]
	v_mfma_f32_16x16x32_bf16 v[78:81], v[166:169], v[200:203], v[78:81]
	v_mfma_f32_16x16x32_bf16 v[74:77], v[158:161], v[208:211], v[74:77]
	v_mfma_f32_16x16x32_bf16 v[70:73], v[166:169], v[208:211], v[70:73]
	v_mfma_f32_16x16x32_bf16 v[98:101], v[162:165], v[186:189], v[98:101]
	v_mfma_f32_16x16x32_bf16 v[94:97], v[170:173], v[186:189], v[94:97]
	v_mfma_f32_16x16x32_bf16 v[90:93], v[162:165], v[194:197], v[90:93]
	v_mfma_f32_16x16x32_bf16 v[86:89], v[170:173], v[194:197], v[86:89]
	v_mfma_f32_16x16x32_bf16 v[82:85], v[162:165], v[204:207], v[82:85]
	v_mfma_f32_16x16x32_bf16 v[78:81], v[170:173], v[204:207], v[78:81]
	v_mfma_f32_16x16x32_bf16 v[74:77], v[162:165], v[212:215], v[74:77]
	v_mfma_f32_16x16x32_bf16 v[70:73], v[170:173], v[212:215], v[70:73]
	s_barrier
	s_add_i32 s46, s67, s53
	s_add_u32 s90, s44, s96
	s_addc_u32 s91, s45, s97
	s_mov_b32 m0, s46
	ds_read_b128 v[174:177], v184 offset:49152
	ds_read_b128 v[186:189], v184 offset:50176
	ds_read_b128 v[190:193], v184 offset:51200
	ds_read_b128 v[194:197], v184 offset:52224
	ds_read_b128 v[200:203], v184 offset:53248
	ds_read_b128 v[204:207], v184 offset:54272
	ds_read_b128 v[208:211], v184 offset:55296
	ds_read_b128 v[212:215], v184 offset:56320
	global_load_lds_dwordx4 v0, s[90:91]
	s_add_i32 m0, s46, 0x2000
	s_add_u32 s44, s44, 0x80080
	s_addc_u32 s45, s45, 0
	s_add_i32 s46, s68, s53
	global_load_lds_dwordx4 v14, s[90:91]
	s_mov_b32 m0, s46
	s_nop 0
	global_load_lds_dwordx4 v0, s[44:45]
	s_add_i32 m0, s46, 0x2000
	s_nop 0
	global_load_lds_dwordx4 v14, s[44:45]
	s_mov_b32 m0, s59
	s_nop 0
	global_load_lds_dwordx4 v0, s[92:93]
	s_mov_b32 m0, s60
	s_nop 0
	global_load_lds_dwordx4 v14, s[92:93]
	s_waitcnt vmcnt(8)
	s_waitcnt lgkmcnt(0)
	s_barrier
	v_mfma_f32_16x16x32_bf16 v[66:69], v[142:145], v[174:177], v[66:69]
	v_mfma_f32_16x16x32_bf16 v[62:65], v[150:153], v[174:177], v[62:65]
	v_mfma_f32_16x16x32_bf16 v[58:61], v[142:145], v[190:193], v[58:61]
	v_mfma_f32_16x16x32_bf16 v[54:57], v[150:153], v[190:193], v[54:57]
	v_mfma_f32_16x16x32_bf16 v[50:53], v[142:145], v[200:203], v[50:53]
	v_mfma_f32_16x16x32_bf16 v[46:49], v[150:153], v[200:203], v[46:49]
	v_mfma_f32_16x16x32_bf16 v[42:45], v[142:145], v[208:211], v[42:45]
	v_mfma_f32_16x16x32_bf16 v[38:41], v[150:153], v[208:211], v[38:41]
	v_mfma_f32_16x16x32_bf16 v[66:69], v[146:149], v[186:189], v[66:69]
	v_mfma_f32_16x16x32_bf16 v[62:65], v[154:157], v[186:189], v[62:65]
	v_mfma_f32_16x16x32_bf16 v[58:61], v[146:149], v[194:197], v[58:61]
	v_mfma_f32_16x16x32_bf16 v[54:57], v[154:157], v[194:197], v[54:57]
	v_mfma_f32_16x16x32_bf16 v[50:53], v[146:149], v[204:207], v[50:53]
	v_mfma_f32_16x16x32_bf16 v[46:49], v[154:157], v[204:207], v[46:49]
	v_mfma_f32_16x16x32_bf16 v[42:45], v[146:149], v[212:215], v[42:45]
	v_mfma_f32_16x16x32_bf16 v[38:41], v[154:157], v[212:215], v[38:41]
	v_mfma_f32_16x16x32_bf16 v[34:37], v[158:161], v[174:177], v[34:37]
	v_mfma_f32_16x16x32_bf16 v[30:33], v[166:169], v[174:177], v[30:33]
	v_mfma_f32_16x16x32_bf16 v[26:29], v[158:161], v[190:193], v[26:29]
	v_mfma_f32_16x16x32_bf16 v[22:25], v[166:169], v[190:193], v[22:25]
	v_mfma_f32_16x16x32_bf16 v[18:21], v[158:161], v[200:203], v[18:21]
	v_mfma_f32_16x16x32_bf16 v[10:13], v[166:169], v[200:203], v[10:13]
	v_mfma_f32_16x16x32_bf16 v[6:9], v[158:161], v[208:211], v[6:9]
	v_mfma_f32_16x16x32_bf16 v[2:5], v[166:169], v[208:211], v[2:5]
	v_mfma_f32_16x16x32_bf16 v[34:37], v[162:165], v[186:189], v[34:37]
	v_mfma_f32_16x16x32_bf16 v[30:33], v[170:173], v[186:189], v[30:33]
	v_mfma_f32_16x16x32_bf16 v[26:29], v[162:165], v[194:197], v[26:29]
	v_mfma_f32_16x16x32_bf16 v[22:25], v[170:173], v[194:197], v[22:25]
	v_mfma_f32_16x16x32_bf16 v[18:21], v[162:165], v[204:207], v[18:21]
	v_mfma_f32_16x16x32_bf16 v[10:13], v[170:173], v[204:207], v[10:13]
	v_mfma_f32_16x16x32_bf16 v[6:9], v[162:165], v[212:215], v[6:9]
	v_mfma_f32_16x16x32_bf16 v[2:5], v[170:173], v[212:215], v[2:5]
	s_barrier
	s_add_i32 s66, s66, 2
	s_add_u32 s40, s40, 0x100
	s_addc_u32 s41, s41, 0
	s_cmp_gt_u32 s66, 29
	s_cbranch_scc0 .LBB0_2399
	s_and_b64 vcc, exec, s[18:19]
	s_cbranch_vccz .LBB0_2402
	s_barrier
